# prologue: W_out transpose item loads all in flight + x->bf16 fast path with next-stage loads issued before processing and DPP/permlane reduction; stacked on previous best
# speedup vs baseline: 1.0384x; 1.0012x over previous
; #define LAS __attribute__((address_space(3)))
; __device__ __forceinline__ void p0_transpose_item(const float* W, int K, int N, bf16* WT, const float* ks, int radd, LAS float* scr, int kb, int nb, int lane) {
;     const int k0 = 64 * kb, n0 = 32 * nb;
; #pragma unroll 8
;     for (int i = 0; i < 32; ++i) { const int kk = 2 * i + (lane >> 5); const float s = ks ? ks[k0 + kk] : 1.0f; scr[kk * 33 + (lane & 31)] = __builtin_nontemporal_load(W + (size_t)(k0 + kk) * N + n0 + (lane & 31)) * s; }
; __device__ __forceinline__ void p0_prologue(const Ptrs& P, LAS unsigned char* lds, int gw, int NGW, int wave, int lane, int gtid, int GT, int part) {
;     ...
;         if (r < I1) { const int nblk = D / 32; p0_transpose_item(P.lwout, LW, D, WO0T, nullptr, 0, scr, r / nblk, r % nblk, lane); continue; } r -= I1;
.LBB0_21:
	s_andn2_b64 vcc, exec, s[2:3]
	s_cbranch_vccnz .LBB0_25
	s_and_b32 s2, s29, 63
	s_lshl_b32 s2, s2, 6
	v_add_u32_e32 v22, s2, v73
	v_add_u32_e32 v24, s2, v74
	v_add_u32_e32 v26, s2, v75
	v_add_u32_e32 v28, s2, v76
	v_add_u32_e32 v30, s2, v77
	v_add_u32_e32 v32, s2, v78
	v_add_u32_e32 v34, s2, v79
	v_add_u32_e32 v36, s2, v80
	v_ashrrev_i32_e32 v23, 31, v22
	v_ashrrev_i32_e32 v25, 31, v24
	v_ashrrev_i32_e32 v27, 31, v26
	v_ashrrev_i32_e32 v29, 31, v28
	v_ashrrev_i32_e32 v31, 31, v30
	v_ashrrev_i32_e32 v33, 31, v32
	v_ashrrev_i32_e32 v35, 31, v34
	v_ashrrev_i32_e32 v37, 31, v36
	v_lshlrev_b64 v[22:23], 12, v[22:23]
	v_lshlrev_b64 v[24:25], 12, v[24:25]
	v_lshlrev_b64 v[26:27], 12, v[26:27]
	v_lshlrev_b64 v[28:29], 12, v[28:29]
	v_lshlrev_b64 v[30:31], 12, v[30:31]
	v_lshlrev_b64 v[32:33], 12, v[32:33]
	v_lshlrev_b64 v[34:35], 12, v[34:35]
	v_lshlrev_b64 v[36:37], 12, v[36:37]
	v_or_b32_e32 v22, s28, v22
	v_or_b32_e32 v24, s28, v24
	v_or_b32_e32 v26, s28, v26
	v_or_b32_e32 v28, s28, v28
	v_or_b32_e32 v30, s28, v30
	v_or_b32_e32 v32, s28, v32
	v_or_b32_e32 v34, s28, v34
	v_or_b32_e32 v36, s28, v36
	v_lshl_add_u64 v[22:23], v[20:21], 0, v[22:23]
	v_lshl_add_u64 v[24:25], v[20:21], 0, v[24:25]
	v_lshl_add_u64 v[26:27], v[20:21], 0, v[26:27]
	v_lshl_add_u64 v[28:29], v[20:21], 0, v[28:29]
	v_lshl_add_u64 v[30:31], v[20:21], 0, v[30:31]
	v_lshl_add_u64 v[32:33], v[20:21], 0, v[32:33]
	v_lshl_add_u64 v[34:35], v[20:21], 0, v[34:35]
	v_lshl_add_u64 v[36:37], v[20:21], 0, v[36:37]
	s_mov_b64 s[2:3], 0
	v_mov_b32_e32 v4, v57
	s_mov_b64 s[2:3], 0
	v_lshl_add_u64 v[38:39], v[36:37], 0, s[2:3]
	v_lshl_add_u64 v[40:41], v[34:35], 0, s[2:3]
	v_lshl_add_u64 v[42:43], v[32:33], 0, s[2:3]
	v_lshl_add_u64 v[44:45], v[30:31], 0, s[2:3]
	v_lshl_add_u64 v[46:47], v[28:29], 0, s[2:3]
	v_lshl_add_u64 v[48:49], v[26:27], 0, s[2:3]
	v_lshl_add_u64 v[50:51], v[24:25], 0, s[2:3]
	v_lshl_add_u64 v[52:53], v[22:23], 0, s[2:3]
	global_load_dword v100, v[38:39], off nt
	global_load_dword v101, v[40:41], off nt
	global_load_dword v102, v[42:43], off nt
	global_load_dword v103, v[44:45], off nt
	global_load_dword v104, v[46:47], off nt
	global_load_dword v105, v[48:49], off nt
	global_load_dword v106, v[50:51], off nt
	global_load_dword v107, v[52:53], off nt
	s_mov_b64 s[2:3], 0x10000
	v_lshl_add_u64 v[38:39], v[36:37], 0, s[2:3]
	v_lshl_add_u64 v[40:41], v[34:35], 0, s[2:3]
	v_lshl_add_u64 v[42:43], v[32:33], 0, s[2:3]
	v_lshl_add_u64 v[44:45], v[30:31], 0, s[2:3]
	v_lshl_add_u64 v[46:47], v[28:29], 0, s[2:3]
	v_lshl_add_u64 v[48:49], v[26:27], 0, s[2:3]
	v_lshl_add_u64 v[50:51], v[24:25], 0, s[2:3]
	v_lshl_add_u64 v[52:53], v[22:23], 0, s[2:3]
	global_load_dword v108, v[38:39], off nt
	global_load_dword v109, v[40:41], off nt
	global_load_dword v110, v[42:43], off nt
	global_load_dword v111, v[44:45], off nt
	global_load_dword v112, v[46:47], off nt
	global_load_dword v113, v[48:49], off nt
	global_load_dword v114, v[50:51], off nt
	global_load_dword v115, v[52:53], off nt
	s_mov_b64 s[2:3], 0x20000
	v_lshl_add_u64 v[38:39], v[36:37], 0, s[2:3]
	v_lshl_add_u64 v[40:41], v[34:35], 0, s[2:3]
	v_lshl_add_u64 v[42:43], v[32:33], 0, s[2:3]
	v_lshl_add_u64 v[44:45], v[30:31], 0, s[2:3]
	v_lshl_add_u64 v[46:47], v[28:29], 0, s[2:3]
	v_lshl_add_u64 v[48:49], v[26:27], 0, s[2:3]
	v_lshl_add_u64 v[50:51], v[24:25], 0, s[2:3]
	v_lshl_add_u64 v[52:53], v[22:23], 0, s[2:3]
	global_load_dword v116, v[38:39], off nt
	global_load_dword v117, v[40:41], off nt
	global_load_dword v118, v[42:43], off nt
	global_load_dword v119, v[44:45], off nt
	global_load_dword v120, v[46:47], off nt
	global_load_dword v121, v[48:49], off nt
	global_load_dword v122, v[50:51], off nt
	global_load_dword v123, v[52:53], off nt
	s_mov_b64 s[2:3], 0x30000
	v_lshl_add_u64 v[38:39], v[36:37], 0, s[2:3]
	v_lshl_add_u64 v[40:41], v[34:35], 0, s[2:3]
	v_lshl_add_u64 v[42:43], v[32:33], 0, s[2:3]
	v_lshl_add_u64 v[44:45], v[30:31], 0, s[2:3]
	v_lshl_add_u64 v[46:47], v[28:29], 0, s[2:3]
	v_lshl_add_u64 v[48:49], v[26:27], 0, s[2:3]
	v_lshl_add_u64 v[50:51], v[24:25], 0, s[2:3]
	v_lshl_add_u64 v[52:53], v[22:23], 0, s[2:3]
	global_load_dword v124, v[38:39], off nt
	global_load_dword v125, v[40:41], off nt
	global_load_dword v126, v[42:43], off nt
	global_load_dword v127, v[44:45], off nt
	global_load_dword v128, v[46:47], off nt
	global_load_dword v129, v[48:49], off nt
	global_load_dword v130, v[50:51], off nt
	global_load_dword v131, v[52:53], off nt
	v_add_u32_e32 v46, 0x400, v4
	s_waitcnt vmcnt(30)
; #define LAS __attribute__((address_space(3)))
; __device__ __forceinline__ unsigned pk2(float lo, float hi) { f32x2_t v = {lo, hi}; bf16x2_t b = __builtin_convertvector(v, bf16x2_t); return __builtin_bit_cast(unsigned, b); }
; #define LDS_WAIT() asm volatile("s_waitcnt lgkmcnt(0)" ::: "memory")
; __device__ __forceinline__ void p0_transpose_item(const float* W, int K, int N, bf16* WT, const float* ks, int radd, LAS float* scr, int kb, int nb, int lane) {
;     ...
;     for (int i = 0; i < 32; ++i) { const int kk = 2 * i + (lane >> 5); const float s = ks ? ks[k0 + kk] : 1.0f; scr[kk * 33 + (lane & 31)] = __builtin_nontemporal_load(W + (size_t)(k0 + kk) * N + n0 + (lane & 31)) * s; }
;     LDS_WAIT(); asm volatile("" ::: "memory");
;     const int c = lane & 7;
; #pragma unroll
;     for (int j = 0; j < 4; ++j) { const int n = (lane >> 3) + 8 * j; const LAS float* s = scr + (8 * c) * 33 + n;
;         v4u o; o.x = pk2(s[0 * 33], s[1 * 33]); o.y = pk2(s[2 * 33], s[3 * 33]); o.z = pk2(s[4 * 33], s[5 * 33]); o.w = pk2(s[6 * 33], s[7 * 33]);
;         *(v4u*)(WT + (size_t)(radd + n0 + n) * K + k0 + 8 * c) = o; }
;     LDS_WAIT(); asm volatile("" ::: "memory");
	ds_write2_b32 v4, v100, v101 offset1:66
	s_waitcnt vmcnt(28)
	ds_write2_b32 v4, v102, v103 offset0:132 offset1:198
	s_waitcnt vmcnt(26)
	ds_write2_b32 v46, v104, v105 offset0:8 offset1:74
	s_waitcnt vmcnt(24)
	ds_write2_b32 v46, v106, v107 offset0:140 offset1:206
	v_add_u32_e32 v4, 0x840, v4
	v_add_u32_e32 v46, 0x400, v4
	s_waitcnt vmcnt(22)
	ds_write2_b32 v4, v108, v109 offset1:66
	s_waitcnt vmcnt(20)
	ds_write2_b32 v4, v110, v111 offset0:132 offset1:198
	s_waitcnt vmcnt(18)
	ds_write2_b32 v46, v112, v113 offset0:8 offset1:74
	s_waitcnt vmcnt(16)
	ds_write2_b32 v46, v114, v115 offset0:140 offset1:206
	v_add_u32_e32 v4, 0x840, v4
	v_add_u32_e32 v46, 0x400, v4
	s_waitcnt vmcnt(14)
	ds_write2_b32 v4, v116, v117 offset1:66
	s_waitcnt vmcnt(12)
	ds_write2_b32 v4, v118, v119 offset0:132 offset1:198
	s_waitcnt vmcnt(10)
	ds_write2_b32 v46, v120, v121 offset0:8 offset1:74
	s_waitcnt vmcnt(8)
	ds_write2_b32 v46, v122, v123 offset0:140 offset1:206
	v_add_u32_e32 v4, 0x840, v4
	v_add_u32_e32 v46, 0x400, v4
	s_waitcnt vmcnt(6)
	ds_write2_b32 v4, v124, v125 offset1:66
	s_waitcnt vmcnt(4)
	ds_write2_b32 v4, v126, v127 offset0:132 offset1:198
	s_waitcnt vmcnt(2)
	ds_write2_b32 v46, v128, v129 offset0:8 offset1:74
	s_waitcnt vmcnt(0)
	ds_write2_b32 v46, v130, v131 offset0:140 offset1:206
	v_add_u32_e32 v4, 0x840, v4
	s_lshl_b32 s2, s74, 1
	s_and_b32 s2, s2, 0xfc0
	s_waitcnt lgkmcnt(0)
	s_add_i32 s4, s2, 0xfffff600
	s_lshl_b32 s2, s74, 5
	s_and_b32 s2, s2, 0x3e0
	ds_read2_b32 v[26:27], v3 offset0:33 offset1:41
	ds_read2_b32 v[28:29], v3 offset1:8
	ds_read2_b32 v[30:31], v3 offset0:66 offset1:74
	ds_read2_b32 v[32:33], v3 offset0:99 offset1:107
	ds_read2_b32 v[34:35], v3 offset0:132 offset1:140
	ds_read2_b32 v[36:37], v3 offset0:165 offset1:173
	ds_read2_b32 v[38:39], v3 offset0:198 offset1:206
	ds_read2_b32 v[40:41], v3 offset0:231 offset1:239
	v_or_b32_e32 v4, s2, v1
	v_mul_u32_u24_e32 v4, 0x500, v4
	v_lshl_add_u64 v[42:43], s[4:5], 1, v[10:11]
	v_lshlrev_b32_e32 v4, 1, v4
	v_lshl_add_u64 v[44:45], v[42:43], 0, v[4:5]
	v_or_b32_e32 v4, s2, v54
	s_waitcnt lgkmcnt(6)
	v_cvt_pk_bf16_f32 v22, v28, v26
	s_waitcnt lgkmcnt(4)
	v_cvt_pk_bf16_f32 v23, v30, v32
	s_waitcnt lgkmcnt(2)
	v_cvt_pk_bf16_f32 v24, v34, v36
	s_waitcnt lgkmcnt(0)
	v_cvt_pk_bf16_f32 v25, v38, v40
	v_mul_u32_u24_e32 v4, 0x500, v4
	global_store_dwordx4 v[44:45], v[22:25], off
	v_lshlrev_b32_e32 v4, 1, v4
	s_nop 0
	v_cvt_pk_bf16_f32 v22, v29, v27
	v_cvt_pk_bf16_f32 v23, v31, v33
	v_cvt_pk_bf16_f32 v24, v35, v37
	v_cvt_pk_bf16_f32 v25, v39, v41
	v_lshl_add_u64 v[26:27], v[42:43], 0, v[4:5]
	ds_read2_b32 v[28:29], v3 offset0:16 offset1:24
	ds_read2_b32 v[30:31], v3 offset0:49 offset1:57
	ds_read2_b32 v[32:33], v3 offset0:82 offset1:90
	ds_read2_b32 v[34:35], v3 offset0:115 offset1:123
	ds_read2_b32 v[36:37], v3 offset0:148 offset1:156
	ds_read2_b32 v[38:39], v3 offset0:181 offset1:189
	ds_read2_b32 v[40:41], v3 offset0:214 offset1:222
	ds_read2_b32 v[44:45], v3 offset0:247 offset1:255
	v_or_b32_e32 v4, s2, v55
	v_mul_u32_u24_e32 v4, 0x500, v4
	v_lshlrev_b32_e32 v4, 1, v4
	global_store_dwordx4 v[26:27], v[22:25], off
	v_lshl_add_u64 v[26:27], v[42:43], 0, v[4:5]
	v_or_b32_e32 v4, s2, v56
	v_mul_u32_u24_e32 v4, 0x500, v4
	s_waitcnt lgkmcnt(6)
	v_cvt_pk_bf16_f32 v22, v28, v30
	s_waitcnt lgkmcnt(4)
	v_cvt_pk_bf16_f32 v23, v32, v34
	s_waitcnt lgkmcnt(2)
	v_cvt_pk_bf16_f32 v24, v36, v38
	s_waitcnt lgkmcnt(0)
	v_cvt_pk_bf16_f32 v25, v40, v44
	v_lshlrev_b32_e32 v4, 1, v4
	global_store_dwordx4 v[26:27], v[22:25], off
	v_lshl_add_u64 v[26:27], v[42:43], 0, v[4:5]
	s_nop 0
	v_cvt_pk_bf16_f32 v22, v29, v31
	v_cvt_pk_bf16_f32 v23, v33, v35
	v_cvt_pk_bf16_f32 v24, v37, v39
	v_cvt_pk_bf16_f32 v25, v41, v45
	global_store_dwordx4 v[26:27], v[22:25], off
	s_waitcnt lgkmcnt(0)

; __device__ __forceinline__ unsigned pk2(float lo, float hi) { f32x2_t v = {lo, hi}; bf16x2_t b = __builtin_convertvector(v, bf16x2_t); return __builtin_bit_cast(unsigned, b); }
; __device__ __forceinline__ void p0_prologue(const Ptrs& P, LAS unsigned char* lds, int gw, int NGW, int wave, int lane, int gtid, int GT, int part) {
;     ...
;     for (int m0 = gw; m0 < M; m0 += 2 * NGW) {
;         f32x4 v[2][4];
; #pragma unroll
;         for (int q = 0; q < 2; ++q) { const int m = m0 + q * NGW; if (m < M) { const f32x4* xr = (const f32x4*)(P.x + (size_t)m * D) + lane;
; #pragma unroll
;             for (int j = 0; j < 4; ++j) v[q][j] = __builtin_nontemporal_load(xr + 64 * j); } }
; #pragma unroll
;         for (int q = 0; q < 2; ++q) { const int m = m0 + q * NGW; if (m < M) { unsigned long long* o8 = (unsigned long long*)(XB + (size_t)m * D) + lane; float s = 0.f;
; #pragma unroll
;             for (int j = 0; j < 4; ++j) { s += (v[q][j].x * v[q][j].x + v[q][j].y * v[q][j].y) + (v[q][j].z * v[q][j].z + v[q][j].w * v[q][j].w);
;                 o8[64 * j] = (unsigned long long)pk2(v[q][j].x, v[q][j].y) | ((unsigned long long)pk2(v[q][j].z, v[q][j].w) << 32); }
;             s = wave_sum(s); if (lane == 0) ssq0[m] = s; } }
.Lp0_skip_tables:
	s_cmpk_lg_i32 s62, 0x800
	s_cbranch_scc1 .Lp0_x_generic
	v_lshlrev_b32_e32 v176, 4, v232
	v_lshlrev_b32_e32 v177, 3, v232
	v_mov_b32_e32 v178, 0
	v_cmp_eq_u32_e64 s[22:23], 0, v232
	s_add_u32 s24, s54, 0x1800000
	s_addc_u32 s25, s55, 0
	s_add_u32 s26, s54, 0x100000
	s_addc_u32 s27, s55, 0
	s_mov_b32 s28, s60
	s_lshl_b32 s2, s28, 12
	s_add_u32 s4, s36, s2
	s_addc_u32 s5, s37, 0
	global_load_dwordx4 v[100:103], v176, s[4:5] nt
	global_load_dwordx4 v[104:107], v176, s[4:5] offset:1024 nt
	global_load_dwordx4 v[108:111], v176, s[4:5] offset:2048 nt
	global_load_dwordx4 v[112:115], v176, s[4:5] offset:3072 nt
	s_add_u32 s4, s4, 0x800000
	s_addc_u32 s5, s5, 0
	global_load_dwordx4 v[116:119], v176, s[4:5] nt
	global_load_dwordx4 v[120:123], v176, s[4:5] offset:1024 nt
	global_load_dwordx4 v[124:127], v176, s[4:5] offset:2048 nt
	global_load_dwordx4 v[128:131], v176, s[4:5] offset:3072 nt
	s_mov_b32 s29, s28
	s_addk_i32 s28, 0x1000
	s_lshl_b32 s2, s28, 12
	s_add_u32 s4, s36, s2
	s_addc_u32 s5, s37, 0
	global_load_dwordx4 v[132:135], v176, s[4:5] nt
	global_load_dwordx4 v[136:139], v176, s[4:5] offset:1024 nt
	global_load_dwordx4 v[140:143], v176, s[4:5] offset:2048 nt
	global_load_dwordx4 v[144:147], v176, s[4:5] offset:3072 nt
	s_add_u32 s4, s4, 0x800000
	s_addc_u32 s5, s5, 0
	global_load_dwordx4 v[148:151], v176, s[4:5] nt
	global_load_dwordx4 v[152:155], v176, s[4:5] offset:1024 nt
	global_load_dwordx4 v[156:159], v176, s[4:5] offset:2048 nt
	global_load_dwordx4 v[160:163], v176, s[4:5] offset:3072 nt
	s_waitcnt vmcnt(12)
	s_lshl_b32 s2, s29, 11
	s_add_u32 s6, s24, s2
	s_addc_u32 s7, s25, 0
	s_lshl_b32 s2, s29, 2
	s_add_u32 s8, s26, s2
	s_addc_u32 s9, s27, 0
	v_mul_f32_e32 v172, v101, v101
	v_mul_f32_e32 v179, v103, v103
	v_fmac_f32_e32 v172, v100, v100
	v_fmac_f32_e32 v179, v102, v102
	v_add_f32_e32 v172, v172, v179
	v_mul_f32_e32 v173, v105, v105
	v_mul_f32_e32 v179, v107, v107
	v_fmac_f32_e32 v173, v104, v104
	v_fmac_f32_e32 v179, v106, v106
	v_add_f32_e32 v173, v173, v179
	v_mul_f32_e32 v174, v109, v109
	v_mul_f32_e32 v179, v111, v111
	v_fmac_f32_e32 v174, v108, v108
	v_fmac_f32_e32 v179, v110, v110
	v_add_f32_e32 v174, v174, v179
	v_mul_f32_e32 v175, v113, v113
	v_mul_f32_e32 v179, v115, v115
	v_fmac_f32_e32 v175, v112, v112
	v_fmac_f32_e32 v179, v114, v114
	v_add_f32_e32 v175, v175, v179
	v_add_f32_e32 v180, v172, v173
	v_add_f32_e32 v180, v180, v174
	v_add_f32_e32 v180, v180, v175
	v_cvt_pk_bf16_f32 v164, v100, v101
	v_cvt_pk_bf16_f32 v165, v102, v103
	v_add_f32_dpp v181, v180, v180 quad_perm:[1,0,3,2] row_mask:0xf bank_mask:0xf
	v_cvt_pk_bf16_f32 v166, v104, v105
	v_cvt_pk_bf16_f32 v167, v106, v107
	v_add_f32_dpp v180, v181, v181 quad_perm:[2,3,0,1] row_mask:0xf bank_mask:0xf
	v_cvt_pk_bf16_f32 v168, v108, v109
	v_cvt_pk_bf16_f32 v169, v110, v111
	v_add_f32_dpp v181, v180, v180 row_half_mirror row_mask:0xf bank_mask:0xf
	v_cvt_pk_bf16_f32 v170, v112, v113
	v_cvt_pk_bf16_f32 v171, v114, v115
	v_add_f32_dpp v180, v181, v181 row_mirror row_mask:0xf bank_mask:0xf
	v_mov_b32_e32 v181, v180
	global_store_dwordx2 v177, v[164:165], s[6:7]
	global_store_dwordx2 v177, v[166:167], s[6:7] offset:512
	v_permlane16_swap_b32_e32 v180, v181
	v_add_f32_e32 v180, v180, v181
	v_mov_b32_e32 v181, v180
	global_store_dwordx2 v177, v[168:169], s[6:7] offset:1024
	global_store_dwordx2 v177, v[170:171], s[6:7] offset:1536
	v_permlane32_swap_b32_e32 v180, v181
	v_add_f32_e32 v180, v180, v181
	s_mov_b64 exec, s[22:23]
	global_store_dword v178, v180, s[8:9]
	s_mov_b64 exec, -1
	s_addk_i32 s29, 0x800
	s_waitcnt vmcnt(13)
	s_lshl_b32 s2, s29, 11
	s_add_u32 s6, s24, s2
	s_addc_u32 s7, s25, 0
	s_lshl_b32 s2, s29, 2
	s_add_u32 s8, s26, s2
	s_addc_u32 s9, s27, 0
	v_mul_f32_e32 v172, v117, v117
	v_mul_f32_e32 v179, v119, v119
	v_fmac_f32_e32 v172, v116, v116
	v_fmac_f32_e32 v179, v118, v118
	v_add_f32_e32 v172, v172, v179
	v_mul_f32_e32 v173, v121, v121
	v_mul_f32_e32 v179, v123, v123
	v_fmac_f32_e32 v173, v120, v120
	v_fmac_f32_e32 v179, v122, v122
	v_add_f32_e32 v173, v173, v179
	v_mul_f32_e32 v174, v125, v125
	v_mul_f32_e32 v179, v127, v127
	v_fmac_f32_e32 v174, v124, v124
	v_fmac_f32_e32 v179, v126, v126
	v_add_f32_e32 v174, v174, v179
	v_mul_f32_e32 v175, v129, v129
	v_mul_f32_e32 v179, v131, v131
	v_fmac_f32_e32 v175, v128, v128
	v_fmac_f32_e32 v179, v130, v130
	v_add_f32_e32 v175, v175, v179
	v_add_f32_e32 v180, v172, v173
	v_add_f32_e32 v180, v180, v174
	v_add_f32_e32 v180, v180, v175
	v_cvt_pk_bf16_f32 v164, v116, v117
	v_cvt_pk_bf16_f32 v165, v118, v119
	v_add_f32_dpp v181, v180, v180 quad_perm:[1,0,3,2] row_mask:0xf bank_mask:0xf
	v_cvt_pk_bf16_f32 v166, v120, v121
	v_cvt_pk_bf16_f32 v167, v122, v123
	v_add_f32_dpp v180, v181, v181 quad_perm:[2,3,0,1] row_mask:0xf bank_mask:0xf
	v_cvt_pk_bf16_f32 v168, v124, v125
	v_cvt_pk_bf16_f32 v169, v126, v127
	v_add_f32_dpp v181, v180, v180 row_half_mirror row_mask:0xf bank_mask:0xf
	v_cvt_pk_bf16_f32 v170, v128, v129
	v_cvt_pk_bf16_f32 v171, v130, v131
	v_add_f32_dpp v180, v181, v181 row_mirror row_mask:0xf bank_mask:0xf
	v_mov_b32_e32 v181, v180
	global_store_dwordx2 v177, v[164:165], s[6:7]
	global_store_dwordx2 v177, v[166:167], s[6:7] offset:512
	v_permlane16_swap_b32_e32 v180, v181
	v_add_f32_e32 v180, v180, v181
	v_mov_b32_e32 v181, v180
	global_store_dwordx2 v177, v[168:169], s[6:7] offset:1024
	global_store_dwordx2 v177, v[170:171], s[6:7] offset:1536
	v_permlane32_swap_b32_e32 v180, v181
	v_add_f32_e32 v180, v180, v181
	s_mov_b64 exec, s[22:23]
	global_store_dword v178, v180, s[8:9]
	s_mov_b64 exec, -1
	s_mov_b32 s29, s28
	s_addk_i32 s28, 0x1000
	s_lshl_b32 s2, s28, 12
	s_add_u32 s4, s36, s2
	s_addc_u32 s5, s37, 0
	global_load_dwordx4 v[100:103], v176, s[4:5] nt
	global_load_dwordx4 v[104:107], v176, s[4:5] offset:1024 nt
	global_load_dwordx4 v[108:111], v176, s[4:5] offset:2048 nt
	global_load_dwordx4 v[112:115], v176, s[4:5] offset:3072 nt
	s_add_u32 s4, s4, 0x800000
	s_addc_u32 s5, s5, 0
	global_load_dwordx4 v[116:119], v176, s[4:5] nt
	global_load_dwordx4 v[120:123], v176, s[4:5] offset:1024 nt
	global_load_dwordx4 v[124:127], v176, s[4:5] offset:2048 nt
	global_load_dwordx4 v[128:131], v176, s[4:5] offset:3072 nt
	s_waitcnt vmcnt(12)
; __device__ __forceinline__ unsigned pk2(float lo, float hi) { f32x2_t v = {lo, hi}; bf16x2_t b = __builtin_convertvector(v, bf16x2_t); return __builtin_bit_cast(unsigned, b); }
; __device__ __forceinline__ void p0_prologue(const Ptrs& P, LAS unsigned char* lds, int gw, int NGW, int wave, int lane, int gtid, int GT, int part) {
;     ...
;     for (int m0 = gw; m0 < M; m0 += 2 * NGW) {
;         f32x4 v[2][4];
; #pragma unroll
;         for (int q = 0; q < 2; ++q) { const int m = m0 + q * NGW; if (m < M) { const f32x4* xr = (const f32x4*)(P.x + (size_t)m * D) + lane;
; #pragma unroll
;             for (int j = 0; j < 4; ++j) v[q][j] = __builtin_nontemporal_load(xr + 64 * j); } }
; #pragma unroll
;         for (int q = 0; q < 2; ++q) { const int m = m0 + q * NGW; if (m < M) { unsigned long long* o8 = (unsigned long long*)(XB + (size_t)m * D) + lane; float s = 0.f;
; #pragma unroll
;             for (int j = 0; j < 4; ++j) { s += (v[q][j].x * v[q][j].x + v[q][j].y * v[q][j].y) + (v[q][j].z * v[q][j].z + v[q][j].w * v[q][j].w);
;                 o8[64 * j] = (unsigned long long)pk2(v[q][j].x, v[q][j].y) | ((unsigned long long)pk2(v[q][j].z, v[q][j].w) << 32); }
;             s = wave_sum(s); if (lane == 0) ssq0[m] = s; } }
	s_lshl_b32 s2, s29, 11
	s_add_u32 s6, s24, s2
	s_addc_u32 s7, s25, 0
	s_lshl_b32 s2, s29, 2
	s_add_u32 s8, s26, s2
	s_addc_u32 s9, s27, 0
	v_mul_f32_e32 v172, v133, v133
	v_mul_f32_e32 v179, v135, v135
	v_fmac_f32_e32 v172, v132, v132
	v_fmac_f32_e32 v179, v134, v134
	v_add_f32_e32 v172, v172, v179
	v_mul_f32_e32 v173, v137, v137
	v_mul_f32_e32 v179, v139, v139
	v_fmac_f32_e32 v173, v136, v136
	v_fmac_f32_e32 v179, v138, v138
	v_add_f32_e32 v173, v173, v179
	v_mul_f32_e32 v174, v141, v141
	v_mul_f32_e32 v179, v143, v143
	v_fmac_f32_e32 v174, v140, v140
	v_fmac_f32_e32 v179, v142, v142
	v_add_f32_e32 v174, v174, v179
	v_mul_f32_e32 v175, v145, v145
	v_mul_f32_e32 v179, v147, v147
	v_fmac_f32_e32 v175, v144, v144
	v_fmac_f32_e32 v179, v146, v146
	v_add_f32_e32 v175, v175, v179
	v_add_f32_e32 v180, v172, v173
	v_add_f32_e32 v180, v180, v174
	v_add_f32_e32 v180, v180, v175
	v_cvt_pk_bf16_f32 v164, v132, v133
	v_cvt_pk_bf16_f32 v165, v134, v135
	v_add_f32_dpp v181, v180, v180 quad_perm:[1,0,3,2] row_mask:0xf bank_mask:0xf
	v_cvt_pk_bf16_f32 v166, v136, v137
	v_cvt_pk_bf16_f32 v167, v138, v139
	v_add_f32_dpp v180, v181, v181 quad_perm:[2,3,0,1] row_mask:0xf bank_mask:0xf
	v_cvt_pk_bf16_f32 v168, v140, v141
	v_cvt_pk_bf16_f32 v169, v142, v143
	v_add_f32_dpp v181, v180, v180 row_half_mirror row_mask:0xf bank_mask:0xf
	v_cvt_pk_bf16_f32 v170, v144, v145
	v_cvt_pk_bf16_f32 v171, v146, v147
	v_add_f32_dpp v180, v181, v181 row_mirror row_mask:0xf bank_mask:0xf
	v_mov_b32_e32 v181, v180
	global_store_dwordx2 v177, v[164:165], s[6:7]
	global_store_dwordx2 v177, v[166:167], s[6:7] offset:512
	v_permlane16_swap_b32_e32 v180, v181
	v_add_f32_e32 v180, v180, v181
	v_mov_b32_e32 v181, v180
	global_store_dwordx2 v177, v[168:169], s[6:7] offset:1024
	global_store_dwordx2 v177, v[170:171], s[6:7] offset:1536
	v_permlane32_swap_b32_e32 v180, v181
	v_add_f32_e32 v180, v180, v181
	s_mov_b64 exec, s[22:23]
	global_store_dword v178, v180, s[8:9]
	s_mov_b64 exec, -1
	s_addk_i32 s29, 0x800
	s_waitcnt vmcnt(13)
	s_lshl_b32 s2, s29, 11
	s_add_u32 s6, s24, s2
	s_addc_u32 s7, s25, 0
	s_lshl_b32 s2, s29, 2
	s_add_u32 s8, s26, s2
	s_addc_u32 s9, s27, 0
	v_mul_f32_e32 v172, v149, v149
	v_mul_f32_e32 v179, v151, v151
	v_fmac_f32_e32 v172, v148, v148
	v_fmac_f32_e32 v179, v150, v150
	v_add_f32_e32 v172, v172, v179
	v_mul_f32_e32 v173, v153, v153
	v_mul_f32_e32 v179, v155, v155
	v_fmac_f32_e32 v173, v152, v152
	v_fmac_f32_e32 v179, v154, v154
	v_add_f32_e32 v173, v173, v179
	v_mul_f32_e32 v174, v157, v157
	v_mul_f32_e32 v179, v159, v159
	v_fmac_f32_e32 v174, v156, v156
	v_fmac_f32_e32 v179, v158, v158
	v_add_f32_e32 v174, v174, v179
	v_mul_f32_e32 v175, v161, v161
	v_mul_f32_e32 v179, v163, v163
	v_fmac_f32_e32 v175, v160, v160
	v_fmac_f32_e32 v179, v162, v162
	v_add_f32_e32 v175, v175, v179
	v_add_f32_e32 v180, v172, v173
	v_add_f32_e32 v180, v180, v174
	v_add_f32_e32 v180, v180, v175
	v_cvt_pk_bf16_f32 v164, v148, v149
	v_cvt_pk_bf16_f32 v165, v150, v151
	v_add_f32_dpp v181, v180, v180 quad_perm:[1,0,3,2] row_mask:0xf bank_mask:0xf
	v_cvt_pk_bf16_f32 v166, v152, v153
	v_cvt_pk_bf16_f32 v167, v154, v155
	v_add_f32_dpp v180, v181, v181 quad_perm:[2,3,0,1] row_mask:0xf bank_mask:0xf
	v_cvt_pk_bf16_f32 v168, v156, v157
	v_cvt_pk_bf16_f32 v169, v158, v159
	v_add_f32_dpp v181, v180, v180 row_half_mirror row_mask:0xf bank_mask:0xf
	v_cvt_pk_bf16_f32 v170, v160, v161
	v_cvt_pk_bf16_f32 v171, v162, v163
	v_add_f32_dpp v180, v181, v181 row_mirror row_mask:0xf bank_mask:0xf
	v_mov_b32_e32 v181, v180
	global_store_dwordx2 v177, v[164:165], s[6:7]
	global_store_dwordx2 v177, v[166:167], s[6:7] offset:512
	v_permlane16_swap_b32_e32 v180, v181
	v_add_f32_e32 v180, v180, v181
	v_mov_b32_e32 v181, v180
	global_store_dwordx2 v177, v[168:169], s[6:7] offset:1024
	global_store_dwordx2 v177, v[170:171], s[6:7] offset:1536
	v_permlane32_swap_b32_e32 v180, v181
	v_add_f32_e32 v180, v180, v181
	s_mov_b64 exec, s[22:23]
	global_store_dword v178, v180, s[8:9]
	s_mov_b64 exec, -1
	s_mov_b32 s29, s28
	s_addk_i32 s28, 0x1000
	s_lshl_b32 s2, s28, 12
	s_add_u32 s4, s36, s2
	s_addc_u32 s5, s37, 0
	global_load_dwordx4 v[132:135], v176, s[4:5] nt
	global_load_dwordx4 v[136:139], v176, s[4:5] offset:1024 nt
	global_load_dwordx4 v[140:143], v176, s[4:5] offset:2048 nt
	global_load_dwordx4 v[144:147], v176, s[4:5] offset:3072 nt
	s_add_u32 s4, s4, 0x800000
	s_addc_u32 s5, s5, 0
	global_load_dwordx4 v[148:151], v176, s[4:5] nt
	global_load_dwordx4 v[152:155], v176, s[4:5] offset:1024 nt
	global_load_dwordx4 v[156:159], v176, s[4:5] offset:2048 nt
	global_load_dwordx4 v[160:163], v176, s[4:5] offset:3072 nt
	s_waitcnt vmcnt(12)
; __device__ __forceinline__ unsigned pk2(float lo, float hi) { f32x2_t v = {lo, hi}; bf16x2_t b = __builtin_convertvector(v, bf16x2_t); return __builtin_bit_cast(unsigned, b); }
; __device__ __forceinline__ void p0_prologue(const Ptrs& P, LAS unsigned char* lds, int gw, int NGW, int wave, int lane, int gtid, int GT, int part) {
;     ...
;     for (int m0 = gw; m0 < M; m0 += 2 * NGW) {
;         f32x4 v[2][4];
; #pragma unroll
;         for (int q = 0; q < 2; ++q) { const int m = m0 + q * NGW; if (m < M) { const f32x4* xr = (const f32x4*)(P.x + (size_t)m * D) + lane;
; #pragma unroll
;             for (int j = 0; j < 4; ++j) v[q][j] = __builtin_nontemporal_load(xr + 64 * j); } }
; #pragma unroll
;         for (int q = 0; q < 2; ++q) { const int m = m0 + q * NGW; if (m < M) { unsigned long long* o8 = (unsigned long long*)(XB + (size_t)m * D) + lane; float s = 0.f;
; #pragma unroll
;             for (int j = 0; j < 4; ++j) { s += (v[q][j].x * v[q][j].x + v[q][j].y * v[q][j].y) + (v[q][j].z * v[q][j].z + v[q][j].w * v[q][j].w);
;                 o8[64 * j] = (unsigned long long)pk2(v[q][j].x, v[q][j].y) | ((unsigned long long)pk2(v[q][j].z, v[q][j].w) << 32); }
;             s = wave_sum(s); if (lane == 0) ssq0[m] = s; } }
	s_lshl_b32 s2, s29, 11
	s_add_u32 s6, s24, s2
	s_addc_u32 s7, s25, 0
	s_lshl_b32 s2, s29, 2
	s_add_u32 s8, s26, s2
	s_addc_u32 s9, s27, 0
	v_mul_f32_e32 v172, v101, v101
	v_mul_f32_e32 v179, v103, v103
	v_fmac_f32_e32 v172, v100, v100
	v_fmac_f32_e32 v179, v102, v102
	v_add_f32_e32 v172, v172, v179
	v_mul_f32_e32 v173, v105, v105
	v_mul_f32_e32 v179, v107, v107
	v_fmac_f32_e32 v173, v104, v104
	v_fmac_f32_e32 v179, v106, v106
	v_add_f32_e32 v173, v173, v179
	v_mul_f32_e32 v174, v109, v109
	v_mul_f32_e32 v179, v111, v111
	v_fmac_f32_e32 v174, v108, v108
	v_fmac_f32_e32 v179, v110, v110
	v_add_f32_e32 v174, v174, v179
	v_mul_f32_e32 v175, v113, v113
	v_mul_f32_e32 v179, v115, v115
	v_fmac_f32_e32 v175, v112, v112
	v_fmac_f32_e32 v179, v114, v114
	v_add_f32_e32 v175, v175, v179
	v_add_f32_e32 v180, v172, v173
	v_add_f32_e32 v180, v180, v174
	v_add_f32_e32 v180, v180, v175
	v_cvt_pk_bf16_f32 v164, v100, v101
	v_cvt_pk_bf16_f32 v165, v102, v103
	v_add_f32_dpp v181, v180, v180 quad_perm:[1,0,3,2] row_mask:0xf bank_mask:0xf
	v_cvt_pk_bf16_f32 v166, v104, v105
	v_cvt_pk_bf16_f32 v167, v106, v107
	v_add_f32_dpp v180, v181, v181 quad_perm:[2,3,0,1] row_mask:0xf bank_mask:0xf
	v_cvt_pk_bf16_f32 v168, v108, v109
	v_cvt_pk_bf16_f32 v169, v110, v111
	v_add_f32_dpp v181, v180, v180 row_half_mirror row_mask:0xf bank_mask:0xf
	v_cvt_pk_bf16_f32 v170, v112, v113
	v_cvt_pk_bf16_f32 v171, v114, v115
	v_add_f32_dpp v180, v181, v181 row_mirror row_mask:0xf bank_mask:0xf
	v_mov_b32_e32 v181, v180
	global_store_dwordx2 v177, v[164:165], s[6:7]
	global_store_dwordx2 v177, v[166:167], s[6:7] offset:512
	v_permlane16_swap_b32_e32 v180, v181
	v_add_f32_e32 v180, v180, v181
	v_mov_b32_e32 v181, v180
	global_store_dwordx2 v177, v[168:169], s[6:7] offset:1024
	global_store_dwordx2 v177, v[170:171], s[6:7] offset:1536
	v_permlane32_swap_b32_e32 v180, v181
	v_add_f32_e32 v180, v180, v181
	s_mov_b64 exec, s[22:23]
	global_store_dword v178, v180, s[8:9]
	s_mov_b64 exec, -1
	s_addk_i32 s29, 0x800
	s_waitcnt vmcnt(13)
	s_lshl_b32 s2, s29, 11
	s_add_u32 s6, s24, s2
	s_addc_u32 s7, s25, 0
	s_lshl_b32 s2, s29, 2
	s_add_u32 s8, s26, s2
	s_addc_u32 s9, s27, 0
	v_mul_f32_e32 v172, v117, v117
	v_mul_f32_e32 v179, v119, v119
	v_fmac_f32_e32 v172, v116, v116
	v_fmac_f32_e32 v179, v118, v118
	v_add_f32_e32 v172, v172, v179
	v_mul_f32_e32 v173, v121, v121
	v_mul_f32_e32 v179, v123, v123
	v_fmac_f32_e32 v173, v120, v120
	v_fmac_f32_e32 v179, v122, v122
	v_add_f32_e32 v173, v173, v179
	v_mul_f32_e32 v174, v125, v125
	v_mul_f32_e32 v179, v127, v127
	v_fmac_f32_e32 v174, v124, v124
	v_fmac_f32_e32 v179, v126, v126
	v_add_f32_e32 v174, v174, v179
	v_mul_f32_e32 v175, v129, v129
	v_mul_f32_e32 v179, v131, v131
	v_fmac_f32_e32 v175, v128, v128
	v_fmac_f32_e32 v179, v130, v130
	v_add_f32_e32 v175, v175, v179
	v_add_f32_e32 v180, v172, v173
	v_add_f32_e32 v180, v180, v174
	v_add_f32_e32 v180, v180, v175
	v_cvt_pk_bf16_f32 v164, v116, v117
	v_cvt_pk_bf16_f32 v165, v118, v119
	v_add_f32_dpp v181, v180, v180 quad_perm:[1,0,3,2] row_mask:0xf bank_mask:0xf
	v_cvt_pk_bf16_f32 v166, v120, v121
	v_cvt_pk_bf16_f32 v167, v122, v123
	v_add_f32_dpp v180, v181, v181 quad_perm:[2,3,0,1] row_mask:0xf bank_mask:0xf
	v_cvt_pk_bf16_f32 v168, v124, v125
	v_cvt_pk_bf16_f32 v169, v126, v127
	v_add_f32_dpp v181, v180, v180 row_half_mirror row_mask:0xf bank_mask:0xf
	v_cvt_pk_bf16_f32 v170, v128, v129
	v_cvt_pk_bf16_f32 v171, v130, v131
	v_add_f32_dpp v180, v181, v181 row_mirror row_mask:0xf bank_mask:0xf
	v_mov_b32_e32 v181, v180
	global_store_dwordx2 v177, v[164:165], s[6:7]
	global_store_dwordx2 v177, v[166:167], s[6:7] offset:512
	v_permlane16_swap_b32_e32 v180, v181
	v_add_f32_e32 v180, v180, v181
	v_mov_b32_e32 v181, v180
	global_store_dwordx2 v177, v[168:169], s[6:7] offset:1024
	global_store_dwordx2 v177, v[170:171], s[6:7] offset:1536
	v_permlane32_swap_b32_e32 v180, v181
	v_add_f32_e32 v180, v180, v181
	s_mov_b64 exec, s[22:23]
	global_store_dword v178, v180, s[8:9]
	s_mov_b64 exec, -1
	s_mov_b32 s29, s28
	s_waitcnt vmcnt(12)
; __device__ __forceinline__ unsigned pk2(float lo, float hi) { f32x2_t v = {lo, hi}; bf16x2_t b = __builtin_convertvector(v, bf16x2_t); return __builtin_bit_cast(unsigned, b); }
; __device__ __forceinline__ void p0_prologue(const Ptrs& P, LAS unsigned char* lds, int gw, int NGW, int wave, int lane, int gtid, int GT, int part) {
;     ...
;     for (int m0 = gw; m0 < M; m0 += 2 * NGW) {
;         f32x4 v[2][4];
; #pragma unroll
;         for (int q = 0; q < 2; ++q) { const int m = m0 + q * NGW; if (m < M) { const f32x4* xr = (const f32x4*)(P.x + (size_t)m * D) + lane;
; #pragma unroll
;             for (int j = 0; j < 4; ++j) v[q][j] = __builtin_nontemporal_load(xr + 64 * j); } }
; #pragma unroll
;         for (int q = 0; q < 2; ++q) { const int m = m0 + q * NGW; if (m < M) { unsigned long long* o8 = (unsigned long long*)(XB + (size_t)m * D) + lane; float s = 0.f;
; #pragma unroll
;             for (int j = 0; j < 4; ++j) { s += (v[q][j].x * v[q][j].x + v[q][j].y * v[q][j].y) + (v[q][j].z * v[q][j].z + v[q][j].w * v[q][j].w);
;                 o8[64 * j] = (unsigned long long)pk2(v[q][j].x, v[q][j].y) | ((unsigned long long)pk2(v[q][j].z, v[q][j].w) << 32); }
;             s = wave_sum(s); if (lane == 0) ssq0[m] = s; } }
	s_lshl_b32 s2, s29, 11
	s_add_u32 s6, s24, s2
	s_addc_u32 s7, s25, 0
	s_lshl_b32 s2, s29, 2
	s_add_u32 s8, s26, s2
	s_addc_u32 s9, s27, 0
	v_mul_f32_e32 v172, v133, v133
	v_mul_f32_e32 v179, v135, v135
	v_fmac_f32_e32 v172, v132, v132
	v_fmac_f32_e32 v179, v134, v134
	v_add_f32_e32 v172, v172, v179
	v_mul_f32_e32 v173, v137, v137
	v_mul_f32_e32 v179, v139, v139
	v_fmac_f32_e32 v173, v136, v136
	v_fmac_f32_e32 v179, v138, v138
	v_add_f32_e32 v173, v173, v179
	v_mul_f32_e32 v174, v141, v141
	v_mul_f32_e32 v179, v143, v143
	v_fmac_f32_e32 v174, v140, v140
	v_fmac_f32_e32 v179, v142, v142
	v_add_f32_e32 v174, v174, v179
	v_mul_f32_e32 v175, v145, v145
	v_mul_f32_e32 v179, v147, v147
	v_fmac_f32_e32 v175, v144, v144
	v_fmac_f32_e32 v179, v146, v146
	v_add_f32_e32 v175, v175, v179
	v_add_f32_e32 v180, v172, v173
	v_add_f32_e32 v180, v180, v174
	v_add_f32_e32 v180, v180, v175
	v_cvt_pk_bf16_f32 v164, v132, v133
	v_cvt_pk_bf16_f32 v165, v134, v135
	v_add_f32_dpp v181, v180, v180 quad_perm:[1,0,3,2] row_mask:0xf bank_mask:0xf
	v_cvt_pk_bf16_f32 v166, v136, v137
	v_cvt_pk_bf16_f32 v167, v138, v139
	v_add_f32_dpp v180, v181, v181 quad_perm:[2,3,0,1] row_mask:0xf bank_mask:0xf
	v_cvt_pk_bf16_f32 v168, v140, v141
	v_cvt_pk_bf16_f32 v169, v142, v143
	v_add_f32_dpp v181, v180, v180 row_half_mirror row_mask:0xf bank_mask:0xf
	v_cvt_pk_bf16_f32 v170, v144, v145
	v_cvt_pk_bf16_f32 v171, v146, v147
	v_add_f32_dpp v180, v181, v181 row_mirror row_mask:0xf bank_mask:0xf
	v_mov_b32_e32 v181, v180
	global_store_dwordx2 v177, v[164:165], s[6:7]
	global_store_dwordx2 v177, v[166:167], s[6:7] offset:512
	v_permlane16_swap_b32_e32 v180, v181
	v_add_f32_e32 v180, v180, v181
	v_mov_b32_e32 v181, v180
	global_store_dwordx2 v177, v[168:169], s[6:7] offset:1024
	global_store_dwordx2 v177, v[170:171], s[6:7] offset:1536
	v_permlane32_swap_b32_e32 v180, v181
	v_add_f32_e32 v180, v180, v181
	s_mov_b64 exec, s[22:23]
	global_store_dword v178, v180, s[8:9]
	s_mov_b64 exec, -1
	s_addk_i32 s29, 0x800
	s_waitcnt vmcnt(13)
	s_lshl_b32 s2, s29, 11
	s_add_u32 s6, s24, s2
	s_addc_u32 s7, s25, 0
	s_lshl_b32 s2, s29, 2
	s_add_u32 s8, s26, s2
	s_addc_u32 s9, s27, 0
	v_mul_f32_e32 v172, v149, v149
	v_mul_f32_e32 v179, v151, v151
	v_fmac_f32_e32 v172, v148, v148
	v_fmac_f32_e32 v179, v150, v150
	v_add_f32_e32 v172, v172, v179
	v_mul_f32_e32 v173, v153, v153
	v_mul_f32_e32 v179, v155, v155
	v_fmac_f32_e32 v173, v152, v152
	v_fmac_f32_e32 v179, v154, v154
	v_add_f32_e32 v173, v173, v179
	v_mul_f32_e32 v174, v157, v157
	v_mul_f32_e32 v179, v159, v159
	v_fmac_f32_e32 v174, v156, v156
	v_fmac_f32_e32 v179, v158, v158
	v_add_f32_e32 v174, v174, v179
	v_mul_f32_e32 v175, v161, v161
	v_mul_f32_e32 v179, v163, v163
	v_fmac_f32_e32 v175, v160, v160
	v_fmac_f32_e32 v179, v162, v162
	v_add_f32_e32 v175, v175, v179
	v_add_f32_e32 v180, v172, v173
	v_add_f32_e32 v180, v180, v174
	v_add_f32_e32 v180, v180, v175
	v_cvt_pk_bf16_f32 v164, v148, v149
	v_cvt_pk_bf16_f32 v165, v150, v151
	v_add_f32_dpp v181, v180, v180 quad_perm:[1,0,3,2] row_mask:0xf bank_mask:0xf
	v_cvt_pk_bf16_f32 v166, v152, v153
	v_cvt_pk_bf16_f32 v167, v154, v155
	v_add_f32_dpp v180, v181, v181 quad_perm:[2,3,0,1] row_mask:0xf bank_mask:0xf
	v_cvt_pk_bf16_f32 v168, v156, v157
	v_cvt_pk_bf16_f32 v169, v158, v159
	v_add_f32_dpp v181, v180, v180 row_half_mirror row_mask:0xf bank_mask:0xf
	v_cvt_pk_bf16_f32 v170, v160, v161
	v_cvt_pk_bf16_f32 v171, v162, v163
	v_add_f32_dpp v180, v181, v181 row_mirror row_mask:0xf bank_mask:0xf
	v_mov_b32_e32 v181, v180
	global_store_dwordx2 v177, v[164:165], s[6:7]
	global_store_dwordx2 v177, v[166:167], s[6:7] offset:512
	v_permlane16_swap_b32_e32 v180, v181
	v_add_f32_e32 v180, v180, v181
	v_mov_b32_e32 v181, v180
	global_store_dwordx2 v177, v[168:169], s[6:7] offset:1024
	global_store_dwordx2 v177, v[170:171], s[6:7] offset:1536
	v_permlane32_swap_b32_e32 v180, v181
	v_add_f32_e32 v180, v180, v181
	s_mov_b64 exec, s[22:23]
	global_store_dword v178, v180, s[8:9]
	s_mov_b64 exec, -1
	s_branch .LBB0_109
